# RMSNorm fast path (pipelined, g preloaded) + compress-task loads batched
# speedup vs baseline: 1.0024x; 1.0024x over previous
.LBB0_444:
	s_lshl_b32 s3, s78, 3
	s_and_b32 s3, s3, 0x7000
	v_and_b32_e32 v0, 0xff0, v65
	v_or_b32_e32 v0, s3, v0
	v_mul_u32_u24_e32 v0, 0x300, v0
	v_readlane_b32 s36, v249, 33
	v_lshlrev_b32_e32 v36, 1, v0
	v_readlane_b32 s37, v249, 34
	s_and_b32 s76, s82, 0xffffff80
	s_ashr_i32 s77, s76, 31
	v_lshl_add_u64 v[0:1], s[36:37], 0, v[36:37]
	v_readlane_b32 s36, v249, 5
	s_ashr_i32 s72, s82, 7
	s_and_b32 s83, s78, 0xfe0
	v_lshl_add_u64 v[0:1], s[76:77], 1, v[0:1]
	v_readlane_b32 s37, v249, 6
	v_lshl_add_u64 v[0:1], v[0:1], 0, v[44:45]
	s_cmpk_lt_u32 s82, 0x80
	v_readlane_b32 s46, v249, 15
	v_readlane_b32 s47, v249, 16
	v_readlane_b32 s48, v249, 17
	v_readlane_b32 s49, v249, 18
	v_readlane_b32 s36, v249, 51
	v_lshl_add_u64 v[54:55], v[0:1], 0, v[46:47]
	s_cselect_b32 s76, s46, s48
	s_cselect_b32 s77, s47, s49
	v_readlane_b32 s37, v249, 52
	v_lshl_add_u64 v[56:57], s[76:77], 0, v[48:49]
	v_lshl_add_u64 v[32:33], s[6:7], 2, v[56:57]
	v_lshl_add_u64 v[34:35], v[54:55], 0, s[36:37]
	s_ashr_i32 s73, s72, 31
	s_lshl_b64 s[84:85], s[72:73], 18
	v_lshl_add_u64 v[52:53], v[38:39], 0, s[84:85]
	s_mov_b64 s[76:77], 0x20000
	s_lshl_b64 s[72:73], s[6:7], 1
	v_lshl_add_u64 v[50:51], v[52:53], 0, s[76:77]
	v_lshl_add_u64 v[58:59], v[52:53], 0, s[72:73]
	v_lshl_add_u64 v[54:55], v[50:51], 0, s[72:73]
	s_movk_i32 s76, 0xc00
	s_mov_b32 s77, 0
	v_lshl_add_u64 v[56:57], v[34:35], 0, s[76:77]
	global_load_dwordx4 v[88:91], v[34:35], off
	global_load_dwordx4 v[92:95], v[32:33], off
	global_load_dwordx4 v[96:99], v[32:33], off offset:16
	global_load_dwordx4 v[100:103], v[58:59], off
	global_load_dwordx4 v[104:107], v[54:55], off
	global_load_dwordx4 v[108:111], v[34:35], off offset:32
	global_load_dwordx4 v[112:115], v[32:33], off offset:64
	global_load_dwordx4 v[116:119], v[32:33], off offset:80
	global_load_dwordx4 v[120:123], v[58:59], off offset:32
	global_load_dwordx4 v[124:127], v[54:55], off offset:32
	global_load_dwordx4 v[128:131], v[34:35], off offset:64
	global_load_dwordx4 v[132:135], v[32:33], off offset:128
	global_load_dwordx4 v[136:139], v[32:33], off offset:144
	global_load_dwordx4 v[140:143], v[58:59], off offset:64
	global_load_dwordx4 v[144:147], v[54:55], off offset:64
	global_load_dwordx4 v[148:151], v[34:35], off offset:96
	global_load_dwordx4 v[152:155], v[32:33], off offset:192
	global_load_dwordx4 v[156:159], v[32:33], off offset:208
	global_load_dwordx4 v[160:163], v[58:59], off offset:96
	global_load_dwordx4 v[164:167], v[54:55], off offset:96
	global_load_dwordx4 v[168:171], v[34:35], off offset:1536
	global_load_dwordx4 v[172:175], v[32:33], off offset:256
	global_load_dwordx4 v[176:179], v[32:33], off offset:272
	global_load_dwordx4 v[180:183], v[58:59], off offset:128
	global_load_dwordx4 v[184:187], v[54:55], off offset:128
	global_load_dwordx4 v[188:191], v[34:35], off offset:1568
	global_load_dwordx4 v[196:199], v[32:33], off offset:320
	global_load_dwordx4 v[204:207], v[32:33], off offset:336
	global_load_dwordx4 v[208:211], v[58:59], off offset:160
	global_load_dwordx4 v[212:215], v[54:55], off offset:160
	global_load_dwordx4 v[216:219], v[34:35], off offset:1600
	global_load_dwordx4 v[220:223], v[32:33], off offset:384
	global_load_dwordx4 v[224:227], v[32:33], off offset:400
	global_load_dwordx4 v[228:231], v[58:59], off offset:192
	global_load_dwordx4 v[232:235], v[54:55], off offset:192
	global_load_dwordx4 v[236:239], v[34:35], off offset:1632
	global_load_dwordx4 v[240:243], v[32:33], off offset:448
	global_load_dwordx4 v[244:247], v[32:33], off offset:464
	global_load_dwordx4 v[72:75], v[58:59], off offset:224
	global_load_dwordx4 v[76:79], v[54:55], off offset:224
	s_waitcnt vmcnt(20)
	v_lshlrev_b32_e32 v84, 16, v88
	v_and_b32_e32 v85, 0xffff0000, v88
	v_lshlrev_b32_e32 v86, 16, v89
	v_and_b32_e32 v87, 0xffff0000, v89
	v_pk_add_f32 v[92:93], v[92:93], v[84:85]
	v_pk_add_f32 v[94:95], v[94:95], v[86:87]
	v_lshlrev_b32_e32 v84, 16, v90
	v_and_b32_e32 v85, 0xffff0000, v90
	v_lshlrev_b32_e32 v86, 16, v91
	v_and_b32_e32 v87, 0xffff0000, v91
	v_pk_add_f32 v[96:97], v[96:97], v[84:85]
	v_pk_add_f32 v[98:99], v[98:99], v[86:87]
	v_cvt_pk_bf16_f32 v80, v92, v93
	v_cvt_pk_bf16_f32 v81, v94, v95
	v_cvt_pk_bf16_f32 v82, v96, v97
	v_cvt_pk_bf16_f32 v83, v98, v99
	s_nop 1
	v_mfma_f32_32x32x16_bf16 v[0:15], v[80:83], v[100:103], 0
	v_mfma_f32_32x32x16_bf16 v[16:31], v[80:83], v[104:107], 0
	v_lshlrev_b32_e32 v84, 16, v108
	v_and_b32_e32 v85, 0xffff0000, v108
	v_lshlrev_b32_e32 v86, 16, v109
	v_and_b32_e32 v87, 0xffff0000, v109
	v_pk_add_f32 v[112:113], v[112:113], v[84:85]
	v_pk_add_f32 v[114:115], v[114:115], v[86:87]
	v_lshlrev_b32_e32 v84, 16, v110
	v_and_b32_e32 v85, 0xffff0000, v110
	v_lshlrev_b32_e32 v86, 16, v111
	v_and_b32_e32 v87, 0xffff0000, v111
	v_pk_add_f32 v[116:117], v[116:117], v[84:85]
	v_pk_add_f32 v[118:119], v[118:119], v[86:87]
	v_cvt_pk_bf16_f32 v80, v112, v113
	v_cvt_pk_bf16_f32 v81, v114, v115
	v_cvt_pk_bf16_f32 v82, v116, v117
	v_cvt_pk_bf16_f32 v83, v118, v119
	s_nop 1
	v_mfma_f32_32x32x16_bf16 v[0:15], v[80:83], v[120:123], v[0:15]
	v_mfma_f32_32x32x16_bf16 v[16:31], v[80:83], v[124:127], v[16:31]
	v_lshlrev_b32_e32 v84, 16, v128
	v_and_b32_e32 v85, 0xffff0000, v128
	v_lshlrev_b32_e32 v86, 16, v129
	v_and_b32_e32 v87, 0xffff0000, v129
	v_pk_add_f32 v[132:133], v[132:133], v[84:85]
	v_pk_add_f32 v[134:135], v[134:135], v[86:87]
	v_lshlrev_b32_e32 v84, 16, v130
	v_and_b32_e32 v85, 0xffff0000, v130
	v_lshlrev_b32_e32 v86, 16, v131
	v_and_b32_e32 v87, 0xffff0000, v131
	v_pk_add_f32 v[136:137], v[136:137], v[84:85]
	v_pk_add_f32 v[138:139], v[138:139], v[86:87]
	v_cvt_pk_bf16_f32 v80, v132, v133
	v_cvt_pk_bf16_f32 v81, v134, v135
	v_cvt_pk_bf16_f32 v82, v136, v137
	v_cvt_pk_bf16_f32 v83, v138, v139
	s_nop 1
	v_mfma_f32_32x32x16_bf16 v[0:15], v[80:83], v[140:143], v[0:15]
	v_mfma_f32_32x32x16_bf16 v[16:31], v[80:83], v[144:147], v[16:31]
	v_lshlrev_b32_e32 v84, 16, v148
	v_and_b32_e32 v85, 0xffff0000, v148
	v_lshlrev_b32_e32 v86, 16, v149
	v_and_b32_e32 v87, 0xffff0000, v149
	v_pk_add_f32 v[152:153], v[152:153], v[84:85]
	v_pk_add_f32 v[154:155], v[154:155], v[86:87]
	v_lshlrev_b32_e32 v84, 16, v150
	v_and_b32_e32 v85, 0xffff0000, v150
	v_lshlrev_b32_e32 v86, 16, v151
	v_and_b32_e32 v87, 0xffff0000, v151
	v_pk_add_f32 v[156:157], v[156:157], v[84:85]
	v_pk_add_f32 v[158:159], v[158:159], v[86:87]
	v_cvt_pk_bf16_f32 v80, v152, v153
	v_cvt_pk_bf16_f32 v81, v154, v155
	v_cvt_pk_bf16_f32 v82, v156, v157
	v_cvt_pk_bf16_f32 v83, v158, v159
	s_nop 1
	v_mfma_f32_32x32x16_bf16 v[0:15], v[80:83], v[160:163], v[0:15]
	v_mfma_f32_32x32x16_bf16 v[16:31], v[80:83], v[164:167], v[16:31]
	global_load_dwordx4 v[88:91], v[34:35], off offset:3072
	global_load_dwordx4 v[92:95], v[32:33], off offset:512
	global_load_dwordx4 v[96:99], v[32:33], off offset:528
	global_load_dwordx4 v[100:103], v[58:59], off offset:256
	global_load_dwordx4 v[104:107], v[54:55], off offset:256
	global_load_dwordx4 v[108:111], v[34:35], off offset:3104
	global_load_dwordx4 v[112:115], v[32:33], off offset:576
	global_load_dwordx4 v[116:119], v[32:33], off offset:592
	global_load_dwordx4 v[120:123], v[58:59], off offset:288
	global_load_dwordx4 v[124:127], v[54:55], off offset:288
	global_load_dwordx4 v[128:131], v[34:35], off offset:3136
	global_load_dwordx4 v[132:135], v[32:33], off offset:640
	global_load_dwordx4 v[136:139], v[32:33], off offset:656
	global_load_dwordx4 v[140:143], v[58:59], off offset:320
	global_load_dwordx4 v[144:147], v[54:55], off offset:320
	global_load_dwordx4 v[148:151], v[34:35], off offset:3168
	global_load_dwordx4 v[152:155], v[32:33], off offset:704
	global_load_dwordx4 v[156:159], v[32:33], off offset:720
	global_load_dwordx4 v[160:163], v[58:59], off offset:352
	global_load_dwordx4 v[164:167], v[54:55], off offset:352
	s_waitcnt vmcnt(20)
	v_lshlrev_b32_e32 v84, 16, v168
	v_and_b32_e32 v85, 0xffff0000, v168
	v_lshlrev_b32_e32 v86, 16, v169
	v_and_b32_e32 v87, 0xffff0000, v169
	v_pk_add_f32 v[172:173], v[172:173], v[84:85]
	v_pk_add_f32 v[174:175], v[174:175], v[86:87]
	v_lshlrev_b32_e32 v84, 16, v170
	v_and_b32_e32 v85, 0xffff0000, v170
	v_lshlrev_b32_e32 v86, 16, v171
	v_and_b32_e32 v87, 0xffff0000, v171
	v_pk_add_f32 v[176:177], v[176:177], v[84:85]
	v_pk_add_f32 v[178:179], v[178:179], v[86:87]
	v_cvt_pk_bf16_f32 v80, v172, v173
	v_cvt_pk_bf16_f32 v81, v174, v175
	v_cvt_pk_bf16_f32 v82, v176, v177
	v_cvt_pk_bf16_f32 v83, v178, v179
	s_nop 1
	v_mfma_f32_32x32x16_bf16 v[0:15], v[80:83], v[180:183], v[0:15]
	v_mfma_f32_32x32x16_bf16 v[16:31], v[80:83], v[184:187], v[16:31]
	v_lshlrev_b32_e32 v84, 16, v188
	v_and_b32_e32 v85, 0xffff0000, v188
	v_lshlrev_b32_e32 v86, 16, v189
	v_and_b32_e32 v87, 0xffff0000, v189
	v_pk_add_f32 v[196:197], v[196:197], v[84:85]
	v_pk_add_f32 v[198:199], v[198:199], v[86:87]
	v_lshlrev_b32_e32 v84, 16, v190
	v_and_b32_e32 v85, 0xffff0000, v190
	v_lshlrev_b32_e32 v86, 16, v191
	v_and_b32_e32 v87, 0xffff0000, v191
	v_pk_add_f32 v[204:205], v[204:205], v[84:85]
	v_pk_add_f32 v[206:207], v[206:207], v[86:87]
	v_cvt_pk_bf16_f32 v80, v196, v197
	v_cvt_pk_bf16_f32 v81, v198, v199
	v_cvt_pk_bf16_f32 v82, v204, v205
	v_cvt_pk_bf16_f32 v83, v206, v207
	s_nop 1
	v_mfma_f32_32x32x16_bf16 v[0:15], v[80:83], v[208:211], v[0:15]
	v_mfma_f32_32x32x16_bf16 v[16:31], v[80:83], v[212:215], v[16:31]
	v_lshlrev_b32_e32 v84, 16, v216
	v_and_b32_e32 v85, 0xffff0000, v216
	v_lshlrev_b32_e32 v86, 16, v217
	v_and_b32_e32 v87, 0xffff0000, v217
	v_pk_add_f32 v[220:221], v[220:221], v[84:85]
	v_pk_add_f32 v[222:223], v[222:223], v[86:87]
	v_lshlrev_b32_e32 v84, 16, v218
	v_and_b32_e32 v85, 0xffff0000, v218
	v_lshlrev_b32_e32 v86, 16, v219
	v_and_b32_e32 v87, 0xffff0000, v219
	v_pk_add_f32 v[224:225], v[224:225], v[84:85]
	v_pk_add_f32 v[226:227], v[226:227], v[86:87]
	v_cvt_pk_bf16_f32 v80, v220, v221
	v_cvt_pk_bf16_f32 v81, v222, v223
	v_cvt_pk_bf16_f32 v82, v224, v225
	v_cvt_pk_bf16_f32 v83, v226, v227
	s_nop 1
	v_mfma_f32_32x32x16_bf16 v[0:15], v[80:83], v[228:231], v[0:15]
	v_mfma_f32_32x32x16_bf16 v[16:31], v[80:83], v[232:235], v[16:31]
	v_lshlrev_b32_e32 v84, 16, v236
	v_and_b32_e32 v85, 0xffff0000, v236
	v_lshlrev_b32_e32 v86, 16, v237
	v_and_b32_e32 v87, 0xffff0000, v237
	v_pk_add_f32 v[240:241], v[240:241], v[84:85]
	v_pk_add_f32 v[242:243], v[242:243], v[86:87]
	v_lshlrev_b32_e32 v84, 16, v238
	v_and_b32_e32 v85, 0xffff0000, v238
	v_lshlrev_b32_e32 v86, 16, v239
	v_and_b32_e32 v87, 0xffff0000, v239
	v_pk_add_f32 v[244:245], v[244:245], v[84:85]
	v_pk_add_f32 v[246:247], v[246:247], v[86:87]
	v_cvt_pk_bf16_f32 v80, v240, v241
	v_cvt_pk_bf16_f32 v81, v242, v243
	v_cvt_pk_bf16_f32 v82, v244, v245
	v_cvt_pk_bf16_f32 v83, v246, v247
	s_nop 1
	v_mfma_f32_32x32x16_bf16 v[0:15], v[80:83], v[72:75], v[0:15]
	v_mfma_f32_32x32x16_bf16 v[16:31], v[80:83], v[76:79], v[16:31]
	global_load_dwordx4 v[168:171], v[56:57], off offset:1536
	global_load_dwordx4 v[172:175], v[32:33], off offset:768
	global_load_dwordx4 v[176:179], v[32:33], off offset:784
	global_load_dwordx4 v[180:183], v[58:59], off offset:384
	global_load_dwordx4 v[184:187], v[54:55], off offset:384
	global_load_dwordx4 v[188:191], v[56:57], off offset:1568
	global_load_dwordx4 v[196:199], v[32:33], off offset:832
	global_load_dwordx4 v[204:207], v[32:33], off offset:848
	global_load_dwordx4 v[208:211], v[58:59], off offset:416
	global_load_dwordx4 v[212:215], v[54:55], off offset:416
	global_load_dwordx4 v[216:219], v[56:57], off offset:1600
	global_load_dwordx4 v[220:223], v[32:33], off offset:896
	global_load_dwordx4 v[224:227], v[32:33], off offset:912
	global_load_dwordx4 v[228:231], v[58:59], off offset:448
	global_load_dwordx4 v[232:235], v[54:55], off offset:448
	global_load_dwordx4 v[236:239], v[56:57], off offset:1632
	global_load_dwordx4 v[240:243], v[32:33], off offset:960
	global_load_dwordx4 v[244:247], v[32:33], off offset:976
	global_load_dwordx4 v[72:75], v[58:59], off offset:480
	global_load_dwordx4 v[76:79], v[54:55], off offset:480
	s_waitcnt vmcnt(20)
	v_lshlrev_b32_e32 v84, 16, v88
	v_and_b32_e32 v85, 0xffff0000, v88
	v_lshlrev_b32_e32 v86, 16, v89
	v_and_b32_e32 v87, 0xffff0000, v89
	v_pk_add_f32 v[92:93], v[92:93], v[84:85]
	v_pk_add_f32 v[94:95], v[94:95], v[86:87]
	v_lshlrev_b32_e32 v84, 16, v90
	v_and_b32_e32 v85, 0xffff0000, v90
	v_lshlrev_b32_e32 v86, 16, v91
	v_and_b32_e32 v87, 0xffff0000, v91
	v_pk_add_f32 v[96:97], v[96:97], v[84:85]
	v_pk_add_f32 v[98:99], v[98:99], v[86:87]
	v_cvt_pk_bf16_f32 v80, v92, v93
	v_cvt_pk_bf16_f32 v81, v94, v95
	v_cvt_pk_bf16_f32 v82, v96, v97
	v_cvt_pk_bf16_f32 v83, v98, v99
	s_nop 1
	v_mfma_f32_32x32x16_bf16 v[0:15], v[80:83], v[100:103], v[0:15]
	v_mfma_f32_32x32x16_bf16 v[16:31], v[80:83], v[104:107], v[16:31]
	v_lshlrev_b32_e32 v84, 16, v108
	v_and_b32_e32 v85, 0xffff0000, v108
	v_lshlrev_b32_e32 v86, 16, v109
	v_and_b32_e32 v87, 0xffff0000, v109
	v_pk_add_f32 v[112:113], v[112:113], v[84:85]
	v_pk_add_f32 v[114:115], v[114:115], v[86:87]
	v_lshlrev_b32_e32 v84, 16, v110
	v_and_b32_e32 v85, 0xffff0000, v110
	v_lshlrev_b32_e32 v86, 16, v111
	v_and_b32_e32 v87, 0xffff0000, v111
	v_pk_add_f32 v[116:117], v[116:117], v[84:85]
	v_pk_add_f32 v[118:119], v[118:119], v[86:87]
	v_cvt_pk_bf16_f32 v80, v112, v113
	v_cvt_pk_bf16_f32 v81, v114, v115
	v_cvt_pk_bf16_f32 v82, v116, v117
	v_cvt_pk_bf16_f32 v83, v118, v119
	s_nop 1
	v_mfma_f32_32x32x16_bf16 v[0:15], v[80:83], v[120:123], v[0:15]
	v_mfma_f32_32x32x16_bf16 v[16:31], v[80:83], v[124:127], v[16:31]
	v_lshlrev_b32_e32 v84, 16, v128
	v_and_b32_e32 v85, 0xffff0000, v128
	v_lshlrev_b32_e32 v86, 16, v129
	v_and_b32_e32 v87, 0xffff0000, v129
	v_pk_add_f32 v[132:133], v[132:133], v[84:85]
	v_pk_add_f32 v[134:135], v[134:135], v[86:87]
	v_lshlrev_b32_e32 v84, 16, v130
	v_and_b32_e32 v85, 0xffff0000, v130
	v_lshlrev_b32_e32 v86, 16, v131
	v_and_b32_e32 v87, 0xffff0000, v131
	v_pk_add_f32 v[136:137], v[136:137], v[84:85]
	v_pk_add_f32 v[138:139], v[138:139], v[86:87]
	v_cvt_pk_bf16_f32 v80, v132, v133
	v_cvt_pk_bf16_f32 v81, v134, v135
	v_cvt_pk_bf16_f32 v82, v136, v137
	v_cvt_pk_bf16_f32 v83, v138, v139
	s_nop 1
	v_mfma_f32_32x32x16_bf16 v[0:15], v[80:83], v[140:143], v[0:15]
	v_mfma_f32_32x32x16_bf16 v[16:31], v[80:83], v[144:147], v[16:31]
	v_lshlrev_b32_e32 v84, 16, v148
	v_and_b32_e32 v85, 0xffff0000, v148
	v_lshlrev_b32_e32 v86, 16, v149
	v_and_b32_e32 v87, 0xffff0000, v149
	v_pk_add_f32 v[152:153], v[152:153], v[84:85]
	v_pk_add_f32 v[154:155], v[154:155], v[86:87]
	v_lshlrev_b32_e32 v84, 16, v150
	v_and_b32_e32 v85, 0xffff0000, v150
	v_lshlrev_b32_e32 v86, 16, v151
	v_and_b32_e32 v87, 0xffff0000, v151
	v_pk_add_f32 v[156:157], v[156:157], v[84:85]
	v_pk_add_f32 v[158:159], v[158:159], v[86:87]
	v_cvt_pk_bf16_f32 v80, v152, v153
	v_cvt_pk_bf16_f32 v81, v154, v155
	v_cvt_pk_bf16_f32 v82, v156, v157
	v_cvt_pk_bf16_f32 v83, v158, v159
	s_nop 1
	v_mfma_f32_32x32x16_bf16 v[0:15], v[80:83], v[160:163], v[0:15]
	v_mfma_f32_32x32x16_bf16 v[16:31], v[80:83], v[164:167], v[16:31]
	s_waitcnt vmcnt(0)
	v_lshlrev_b32_e32 v84, 16, v168
	v_and_b32_e32 v85, 0xffff0000, v168
	v_lshlrev_b32_e32 v86, 16, v169
	v_and_b32_e32 v87, 0xffff0000, v169
	v_pk_add_f32 v[172:173], v[172:173], v[84:85]
	v_pk_add_f32 v[174:175], v[174:175], v[86:87]
	v_lshlrev_b32_e32 v84, 16, v170
	v_and_b32_e32 v85, 0xffff0000, v170
	v_lshlrev_b32_e32 v86, 16, v171
	v_and_b32_e32 v87, 0xffff0000, v171
	v_pk_add_f32 v[176:177], v[176:177], v[84:85]
	v_pk_add_f32 v[178:179], v[178:179], v[86:87]
	v_cvt_pk_bf16_f32 v80, v172, v173
	v_cvt_pk_bf16_f32 v81, v174, v175
	v_cvt_pk_bf16_f32 v82, v176, v177
	v_cvt_pk_bf16_f32 v83, v178, v179
	s_nop 1
	v_mfma_f32_32x32x16_bf16 v[0:15], v[80:83], v[180:183], v[0:15]
	v_mfma_f32_32x32x16_bf16 v[16:31], v[80:83], v[184:187], v[16:31]
	v_lshlrev_b32_e32 v84, 16, v188
	v_and_b32_e32 v85, 0xffff0000, v188
	v_lshlrev_b32_e32 v86, 16, v189
	v_and_b32_e32 v87, 0xffff0000, v189
	v_pk_add_f32 v[196:197], v[196:197], v[84:85]
	v_pk_add_f32 v[198:199], v[198:199], v[86:87]
	v_lshlrev_b32_e32 v84, 16, v190
	v_and_b32_e32 v85, 0xffff0000, v190
	v_lshlrev_b32_e32 v86, 16, v191
	v_and_b32_e32 v87, 0xffff0000, v191
	v_pk_add_f32 v[204:205], v[204:205], v[84:85]
	v_pk_add_f32 v[206:207], v[206:207], v[86:87]
	v_cvt_pk_bf16_f32 v80, v196, v197
	v_cvt_pk_bf16_f32 v81, v198, v199
	v_cvt_pk_bf16_f32 v82, v204, v205
	v_cvt_pk_bf16_f32 v83, v206, v207
	s_nop 1
	v_mfma_f32_32x32x16_bf16 v[0:15], v[80:83], v[208:211], v[0:15]
	v_mfma_f32_32x32x16_bf16 v[16:31], v[80:83], v[212:215], v[16:31]
	v_lshlrev_b32_e32 v84, 16, v216
	v_and_b32_e32 v85, 0xffff0000, v216
	v_lshlrev_b32_e32 v86, 16, v217
	v_and_b32_e32 v87, 0xffff0000, v217
	v_pk_add_f32 v[220:221], v[220:221], v[84:85]
	v_pk_add_f32 v[222:223], v[222:223], v[86:87]
	v_lshlrev_b32_e32 v84, 16, v218
	v_and_b32_e32 v85, 0xffff0000, v218
	v_lshlrev_b32_e32 v86, 16, v219
	v_and_b32_e32 v87, 0xffff0000, v219
	v_pk_add_f32 v[224:225], v[224:225], v[84:85]
	v_pk_add_f32 v[226:227], v[226:227], v[86:87]
	v_cvt_pk_bf16_f32 v80, v220, v221
	v_cvt_pk_bf16_f32 v81, v222, v223
	v_cvt_pk_bf16_f32 v82, v224, v225
	v_cvt_pk_bf16_f32 v83, v226, v227
	s_nop 1
	v_mfma_f32_32x32x16_bf16 v[0:15], v[80:83], v[228:231], v[0:15]
	v_mfma_f32_32x32x16_bf16 v[16:31], v[80:83], v[232:235], v[16:31]
	v_lshlrev_b32_e32 v84, 16, v236
	v_and_b32_e32 v85, 0xffff0000, v236
	v_lshlrev_b32_e32 v86, 16, v237
	v_and_b32_e32 v87, 0xffff0000, v237
	v_pk_add_f32 v[240:241], v[240:241], v[84:85]
	v_pk_add_f32 v[242:243], v[242:243], v[86:87]
	v_lshlrev_b32_e32 v84, 16, v238
	v_and_b32_e32 v85, 0xffff0000, v238
	v_lshlrev_b32_e32 v86, 16, v239
	v_and_b32_e32 v87, 0xffff0000, v239
	v_pk_add_f32 v[244:245], v[244:245], v[84:85]
	v_pk_add_f32 v[246:247], v[246:247], v[86:87]
	v_cvt_pk_bf16_f32 v80, v240, v241
	v_cvt_pk_bf16_f32 v81, v242, v243
	v_cvt_pk_bf16_f32 v82, v244, v245
	v_cvt_pk_bf16_f32 v83, v246, v247
	s_nop 1
	v_mfma_f32_32x32x16_bf16 v[0:15], v[80:83], v[72:75], v[0:15]
	v_mfma_f32_32x32x16_bf16 v[16:31], v[80:83], v[76:79], v[16:31]
	s_mov_b64 s[72:73], -1
	s_movk_i32 s3, 0xff
	s_cmpk_gt_u32 s82, 0x7f
	s_nop 11
	ds_write2_b32 v60, v0, v16 offset1:32
	ds_write2_b32 v60, v1, v17 offset0:64 offset1:96
	ds_write2_b32 v60, v2, v18 offset0:128 offset1:160
	ds_write2_b32 v60, v3, v19 offset0:192 offset1:224
	ds_write2_b32 v67, v4, v20 offset1:32
	ds_write2_b32 v67, v5, v21 offset0:64 offset1:96
	ds_write2_b32 v67, v6, v22 offset0:128 offset1:160
	ds_write2_b32 v67, v7, v23 offset0:192 offset1:224
	ds_write2_b32 v68, v8, v24 offset1:32
	ds_write2_b32 v68, v9, v25 offset0:64 offset1:96
	ds_write2_b32 v68, v10, v26 offset0:128 offset1:160
	ds_write2_b32 v68, v11, v27 offset0:192 offset1:224
	ds_write2_b32 v69, v12, v28 offset1:32
	ds_write2_b32 v69, v13, v29 offset0:64 offset1:96
	ds_write2_b32 v69, v14, v30 offset0:128 offset1:160
	ds_write2_b32 v69, v15, v31 offset0:192 offset1:224
	s_waitcnt lgkmcnt(0)
	s_barrier
	ds_read_b128 v[0:3], v62
	s_waitcnt lgkmcnt(0)
	v_pk_add_f32 v[4:5], v[2:3], 0 op_sel_hi:[1,0]
	v_pk_add_f32 v[6:7], v[0:1], 0 op_sel_hi:[1,0]
	ds_read_b128 v[0:3], v62 offset:8192
	s_waitcnt lgkmcnt(0)
	v_pk_add_f32 v[4:5], v[4:5], v[2:3]
	v_pk_add_f32 v[6:7], v[6:7], v[0:1]
	ds_read_b128 v[0:3], v62 offset:16384
	s_waitcnt lgkmcnt(0)
	v_pk_add_f32 v[4:5], v[4:5], v[2:3]
	v_pk_add_f32 v[6:7], v[6:7], v[0:1]
	ds_read_b128 v[0:3], v62 offset:24576
	s_waitcnt lgkmcnt(0)
	v_pk_add_f32 v[4:5], v[4:5], v[2:3]
	v_pk_add_f32 v[6:7], v[6:7], v[0:1]
	ds_read_b128 v[0:3], v62 offset:32768
	s_waitcnt lgkmcnt(0)
	v_pk_add_f32 v[4:5], v[4:5], v[2:3]
	v_pk_add_f32 v[6:7], v[6:7], v[0:1]
	ds_read_b128 v[0:3], v62 offset:40960
	s_waitcnt lgkmcnt(0)
	v_pk_add_f32 v[4:5], v[4:5], v[2:3]
	v_pk_add_f32 v[6:7], v[6:7], v[0:1]
	ds_read_b128 v[0:3], v62 offset:49152
	s_waitcnt lgkmcnt(0)
	v_pk_add_f32 v[4:5], v[4:5], v[2:3]
	v_pk_add_f32 v[6:7], v[6:7], v[0:1]
	ds_read_b128 v[0:3], v62 offset:57344
	s_waitcnt lgkmcnt(0)
	v_pk_add_f32 v[8:9], v[4:5], v[2:3]
	v_add_u16_e32 v2, s83, v61
	v_lshrrev_b16_e32 v2, 1, v2
	v_and_b32_e32 v5, 0xff, v2
	v_pk_add_f32 v[0:1], v[6:7], v[0:1]
	v_cmp_ne_u32_e32 vcc, s3, v5
	v_add_u32_e32 v4, s83, v61
	s_nop 0
	v_cndmask_b32_e32 v3, 0, v1, vcc
	v_cndmask_b32_e32 v2, 0, v0, vcc
	v_cndmask_b32_e32 v1, 0, v9, vcc
	v_cndmask_b32_e32 v0, 0, v8, vcc
	s_cbranch_scc0 .LBB0_446
	v_lshrrev_b32_e32 v6, 2, v4
	s_movk_i32 s3, 0x780
	v_and_or_b32 v6, v6, s3, v64
	v_readlane_b32 s36, v249, 49
	v_lshlrev_b32_e32 v36, 9, v6
	v_readlane_b32 s37, v249, 50
	v_cvt_pk_bf16_f32 v8, v2, v3
	v_cvt_pk_bf16_f32 v9, v0, v1
	v_lshl_add_u64 v[6:7], s[36:37], 0, v[36:37]
	v_lshlrev_b32_e32 v36, 1, v5
	v_lshl_add_u64 v[6:7], v[6:7], 0, v[36:37]
	global_store_short v[6:7], v8, off
	global_store_short_d16_hi v[6:7], v8, off offset:512
	global_store_short v[6:7], v9, off offset:1024
	global_store_short_d16_hi v[6:7], v9, off offset:1536
	s_mov_b64 s[72:73], 0
